# residual GEMM epilogue (bf16 in/out variant) hand-written: all residual loads up front, quad-contiguous rows via ds_bpermute, batched row-sum atomics
# baseline (speedup 1.0000x reference)
.LBB0_200:
	v_readfirstlane_b32 s1, v184
	v_readfirstlane_b32 s4, v182
	v_mbcnt_lo_u32_b32 v100, -1, 0
	v_mbcnt_hi_u32_b32 v100, -1, v100
	s_lshl_b32 s28, s1, 11
	s_lshl_b32 s29, s4, 1
	s_add_i32 s28, s28, s29
	s_add_u32 s28, s58, s28
	s_addc_u32 s29, s59, 0
	v_lshrrev_b32_e32 v234, 2, v100
	v_and_b32_e32 v235, 3, v100
	v_lshlrev_b32_e32 v235, 4, v235
	v_lshl_or_b32 v234, v234, 11, v235
	s_mov_b64 s[30:31], s[28:29]
	global_load_dwordx4 v[130:133], v234, s[30:31]
	global_load_dwordx4 v[134:137], v234, s[30:31] offset:256
	s_add_u32 s30, s30, 0x8000
	s_addc_u32 s31, s31, 0
	global_load_dwordx4 v[138:141], v234, s[30:31]
	global_load_dwordx4 v[142:145], v234, s[30:31] offset:256
	s_add_u32 s30, s30, 0x8000
	s_addc_u32 s31, s31, 0
	global_load_dwordx4 v[146:149], v234, s[30:31]
	global_load_dwordx4 v[150:153], v234, s[30:31] offset:256
	s_add_u32 s30, s30, 0x8000
	s_addc_u32 s31, s31, 0
	global_load_dwordx4 v[154:157], v234, s[30:31]
	global_load_dwordx4 v[158:161], v234, s[30:31] offset:256
	s_add_u32 s30, s30, 0x28000
	s_addc_u32 s31, s31, 0
	global_load_dwordx4 v[162:165], v234, s[30:31]
	global_load_dwordx4 v[166:169], v234, s[30:31] offset:256
	s_add_u32 s30, s30, 0x8000
	s_addc_u32 s31, s31, 0
	global_load_dwordx4 v[182:185], v234, s[30:31]
	global_load_dwordx4 v[186:189], v234, s[30:31] offset:256
	s_add_u32 s30, s30, 0x8000
	s_addc_u32 s31, s31, 0
	global_load_dwordx4 v[200:203], v234, s[30:31]
	global_load_dwordx4 v[208:211], v234, s[30:31] offset:256
	s_add_u32 s30, s30, 0x8000
	s_addc_u32 s31, s31, 0
	global_load_dwordx4 v[226:229], v234, s[30:31]
	global_load_dwordx4 v[230:233], v234, s[30:31] offset:256
	v_and_b32_e32 v212, 15, v100
	v_lshrrev_b32_e32 v235, 4, v100
	v_lshlrev_b32_e32 v235, 2, v235
	v_lshl_or_b32 v212, v212, 4, v235
	v_and_b32_e32 v235, 3, v100
	v_lshlrev_b32_e32 v235, 6, v235
	v_and_or_b32 v213, v100, 60, v235
	v_lshlrev_b32_e32 v100, 2, v100
	s_mov_b64 s[30:31], s[28:29]
	s_waitcnt vmcnt(15)
	ds_bpermute_b32 v130, v212, v130
	ds_bpermute_b32 v131, v212, v131
	ds_bpermute_b32 v132, v212, v132
	ds_bpermute_b32 v133, v212, v133
	s_waitcnt vmcnt(14)
	ds_bpermute_b32 v134, v212, v134
	ds_bpermute_b32 v135, v212, v135
	ds_bpermute_b32 v136, v212, v136
	ds_bpermute_b32 v137, v212, v137
	s_waitcnt lgkmcnt(4)
	v_mov_b32_e32 v192, 0
	v_mov_b32_e32 v193, 0
	v_lshlrev_b32_e32 v204, 16, v130
	v_and_b32_e32 v205, 0xffff0000, v130
	v_pk_add_f32 v[126:127], v[126:127], v[204:205]
	v_pk_fma_f32 v[192:193], v[126:127], v[126:127], v[192:193]
	v_lshlrev_b32_e32 v190, 16, v131
	v_and_b32_e32 v191, 0xffff0000, v131
	v_pk_add_f32 v[128:129], v[128:129], v[190:191]
	v_pk_fma_f32 v[192:193], v[128:129], v[128:129], v[192:193]
	v_lshlrev_b32_e32 v204, 16, v132
	v_and_b32_e32 v205, 0xffff0000, v132
	v_pk_add_f32 v[122:123], v[122:123], v[204:205]
	v_pk_fma_f32 v[192:193], v[122:123], v[122:123], v[192:193]
	v_lshlrev_b32_e32 v190, 16, v133
	v_and_b32_e32 v191, 0xffff0000, v133
	v_pk_add_f32 v[124:125], v[124:125], v[190:191]
	v_pk_fma_f32 v[192:193], v[124:125], v[124:125], v[192:193]
	v_cvt_pk_bf16_f32 v126, v126, v127
	v_cvt_pk_bf16_f32 v127, v128, v129
	v_cvt_pk_bf16_f32 v128, v122, v123
	v_cvt_pk_bf16_f32 v129, v124, v125
	ds_bpermute_b32 v122, v213, v126
	ds_bpermute_b32 v123, v213, v127
	ds_bpermute_b32 v124, v213, v128
	ds_bpermute_b32 v125, v213, v129
	s_waitcnt vmcnt(13)
	ds_bpermute_b32 v138, v212, v138
	ds_bpermute_b32 v139, v212, v139
	ds_bpermute_b32 v140, v212, v140
	ds_bpermute_b32 v141, v212, v141
	s_waitcnt lgkmcnt(8)
	v_lshlrev_b32_e32 v204, 16, v134
	v_and_b32_e32 v205, 0xffff0000, v134
	v_pk_add_f32 v[118:119], v[118:119], v[204:205]
	v_pk_fma_f32 v[192:193], v[118:119], v[118:119], v[192:193]
	v_lshlrev_b32_e32 v190, 16, v135
	v_and_b32_e32 v191, 0xffff0000, v135
	v_pk_add_f32 v[120:121], v[120:121], v[190:191]
	v_pk_fma_f32 v[192:193], v[120:121], v[120:121], v[192:193]
	v_lshlrev_b32_e32 v204, 16, v136
	v_and_b32_e32 v205, 0xffff0000, v136
	v_pk_add_f32 v[114:115], v[114:115], v[204:205]
	v_pk_fma_f32 v[192:193], v[114:115], v[114:115], v[192:193]
	v_lshlrev_b32_e32 v190, 16, v137
	v_and_b32_e32 v191, 0xffff0000, v137
	v_pk_add_f32 v[116:117], v[116:117], v[190:191]
	v_pk_fma_f32 v[192:193], v[116:117], v[116:117], v[192:193]
	v_cvt_pk_bf16_f32 v118, v118, v119
	v_cvt_pk_bf16_f32 v119, v120, v121
	v_cvt_pk_bf16_f32 v120, v114, v115
	v_cvt_pk_bf16_f32 v121, v116, v117
	ds_bpermute_b32 v114, v213, v118
	ds_bpermute_b32 v115, v213, v119
	ds_bpermute_b32 v116, v213, v120
	ds_bpermute_b32 v117, v213, v121
	v_add_f32_e32 v130, v192, v193
	s_waitcnt lgkmcnt(8)
	global_store_dwordx4 v234, v[122:125], s[30:31]
	s_waitcnt vmcnt(13)
	ds_bpermute_b32 v142, v212, v142
	ds_bpermute_b32 v143, v212, v143
	ds_bpermute_b32 v144, v212, v144
	ds_bpermute_b32 v145, v212, v145
	s_waitcnt lgkmcnt(8)
	v_mov_b32_e32 v192, 0
	v_mov_b32_e32 v193, 0
	v_lshlrev_b32_e32 v204, 16, v138
	v_and_b32_e32 v205, 0xffff0000, v138
	v_pk_add_f32 v[110:111], v[110:111], v[204:205]
	v_pk_fma_f32 v[192:193], v[110:111], v[110:111], v[192:193]
	v_lshlrev_b32_e32 v190, 16, v139
	v_and_b32_e32 v191, 0xffff0000, v139
	v_pk_add_f32 v[112:113], v[112:113], v[190:191]
	v_pk_fma_f32 v[192:193], v[112:113], v[112:113], v[192:193]
	v_lshlrev_b32_e32 v204, 16, v140
	v_and_b32_e32 v205, 0xffff0000, v140
	v_pk_add_f32 v[106:107], v[106:107], v[204:205]
	v_pk_fma_f32 v[192:193], v[106:107], v[106:107], v[192:193]
	v_lshlrev_b32_e32 v190, 16, v141
	v_and_b32_e32 v191, 0xffff0000, v141
	v_pk_add_f32 v[108:109], v[108:109], v[190:191]
	v_pk_fma_f32 v[192:193], v[108:109], v[108:109], v[192:193]
	v_cvt_pk_bf16_f32 v110, v110, v111
	v_cvt_pk_bf16_f32 v111, v112, v113
	v_cvt_pk_bf16_f32 v112, v106, v107
	v_cvt_pk_bf16_f32 v113, v108, v109
	ds_bpermute_b32 v106, v213, v110
	ds_bpermute_b32 v107, v213, v111
	ds_bpermute_b32 v108, v213, v112
	ds_bpermute_b32 v109, v213, v113
	s_waitcnt lgkmcnt(8)
	global_store_dwordx4 v234, v[114:117], s[30:31] offset:256
	s_add_u32 s30, s30, 0x8000
	s_addc_u32 s31, s31, 0
	s_waitcnt vmcnt(13)
	ds_bpermute_b32 v146, v212, v146
	ds_bpermute_b32 v147, v212, v147
	ds_bpermute_b32 v148, v212, v148
	ds_bpermute_b32 v149, v212, v149
	s_waitcnt lgkmcnt(8)
	v_lshlrev_b32_e32 v204, 16, v142
	v_and_b32_e32 v205, 0xffff0000, v142
	v_pk_add_f32 v[102:103], v[102:103], v[204:205]
	v_pk_fma_f32 v[192:193], v[102:103], v[102:103], v[192:193]
	v_lshlrev_b32_e32 v190, 16, v143
	v_and_b32_e32 v191, 0xffff0000, v143
	v_pk_add_f32 v[104:105], v[104:105], v[190:191]
	v_pk_fma_f32 v[192:193], v[104:105], v[104:105], v[192:193]
	v_lshlrev_b32_e32 v204, 16, v144
	v_and_b32_e32 v205, 0xffff0000, v144
	v_pk_add_f32 v[96:97], v[96:97], v[204:205]
	v_pk_fma_f32 v[192:193], v[96:97], v[96:97], v[192:193]
	v_lshlrev_b32_e32 v190, 16, v145
	v_and_b32_e32 v191, 0xffff0000, v145
	v_pk_add_f32 v[98:99], v[98:99], v[190:191]
	v_pk_fma_f32 v[192:193], v[98:99], v[98:99], v[192:193]
	v_cvt_pk_bf16_f32 v102, v102, v103
	v_cvt_pk_bf16_f32 v103, v104, v105
	v_cvt_pk_bf16_f32 v104, v96, v97
	v_cvt_pk_bf16_f32 v105, v98, v99
	ds_bpermute_b32 v96, v213, v102
	ds_bpermute_b32 v97, v213, v103
	ds_bpermute_b32 v98, v213, v104
	ds_bpermute_b32 v99, v213, v105
	v_add_f32_e32 v138, v192, v193
	s_waitcnt lgkmcnt(8)
	global_store_dwordx4 v234, v[106:109], s[30:31]
	s_waitcnt vmcnt(13)
	ds_bpermute_b32 v150, v212, v150
	ds_bpermute_b32 v151, v212, v151
	ds_bpermute_b32 v152, v212, v152
	ds_bpermute_b32 v153, v212, v153
	s_waitcnt lgkmcnt(8)
	v_mov_b32_e32 v192, 0
	v_mov_b32_e32 v193, 0
	v_lshlrev_b32_e32 v204, 16, v146
	v_and_b32_e32 v205, 0xffff0000, v146
	v_pk_add_f32 v[92:93], v[92:93], v[204:205]
	v_pk_fma_f32 v[192:193], v[92:93], v[92:93], v[192:193]
	v_lshlrev_b32_e32 v190, 16, v147
	v_and_b32_e32 v191, 0xffff0000, v147
	v_pk_add_f32 v[94:95], v[94:95], v[190:191]
	v_pk_fma_f32 v[192:193], v[94:95], v[94:95], v[192:193]
	v_lshlrev_b32_e32 v204, 16, v148
	v_and_b32_e32 v205, 0xffff0000, v148
	v_pk_add_f32 v[88:89], v[88:89], v[204:205]
	v_pk_fma_f32 v[192:193], v[88:89], v[88:89], v[192:193]
	v_lshlrev_b32_e32 v190, 16, v149
	v_and_b32_e32 v191, 0xffff0000, v149
	v_pk_add_f32 v[90:91], v[90:91], v[190:191]
	v_pk_fma_f32 v[192:193], v[90:91], v[90:91], v[192:193]
	v_cvt_pk_bf16_f32 v92, v92, v93
	v_cvt_pk_bf16_f32 v93, v94, v95
	v_cvt_pk_bf16_f32 v94, v88, v89
	v_cvt_pk_bf16_f32 v95, v90, v91
	ds_bpermute_b32 v88, v213, v92
	ds_bpermute_b32 v89, v213, v93
	ds_bpermute_b32 v90, v213, v94
	ds_bpermute_b32 v91, v213, v95
	s_waitcnt lgkmcnt(8)
	global_store_dwordx4 v234, v[96:99], s[30:31] offset:256
	s_add_u32 s30, s30, 0x8000
	s_addc_u32 s31, s31, 0
	s_waitcnt vmcnt(13)
	ds_bpermute_b32 v154, v212, v154
	ds_bpermute_b32 v155, v212, v155
	ds_bpermute_b32 v156, v212, v156
	ds_bpermute_b32 v157, v212, v157
	s_waitcnt lgkmcnt(8)
	v_lshlrev_b32_e32 v204, 16, v150
	v_and_b32_e32 v205, 0xffff0000, v150
	v_pk_add_f32 v[84:85], v[84:85], v[204:205]
	v_pk_fma_f32 v[192:193], v[84:85], v[84:85], v[192:193]
	v_lshlrev_b32_e32 v190, 16, v151
	v_and_b32_e32 v191, 0xffff0000, v151
	v_pk_add_f32 v[86:87], v[86:87], v[190:191]
	v_pk_fma_f32 v[192:193], v[86:87], v[86:87], v[192:193]
	v_lshlrev_b32_e32 v204, 16, v152
	v_and_b32_e32 v205, 0xffff0000, v152
	v_pk_add_f32 v[80:81], v[80:81], v[204:205]
	v_pk_fma_f32 v[192:193], v[80:81], v[80:81], v[192:193]
	v_lshlrev_b32_e32 v190, 16, v153
	v_and_b32_e32 v191, 0xffff0000, v153
	v_pk_add_f32 v[82:83], v[82:83], v[190:191]
	v_pk_fma_f32 v[192:193], v[82:83], v[82:83], v[192:193]
	v_cvt_pk_bf16_f32 v84, v84, v85
	v_cvt_pk_bf16_f32 v85, v86, v87
	v_cvt_pk_bf16_f32 v86, v80, v81
	v_cvt_pk_bf16_f32 v87, v82, v83
	ds_bpermute_b32 v80, v213, v84
	ds_bpermute_b32 v81, v213, v85
	ds_bpermute_b32 v82, v213, v86
	ds_bpermute_b32 v83, v213, v87
	v_add_f32_e32 v146, v192, v193
	s_waitcnt lgkmcnt(8)
	global_store_dwordx4 v234, v[88:91], s[30:31]
	s_waitcnt vmcnt(13)
	ds_bpermute_b32 v158, v212, v158
	ds_bpermute_b32 v159, v212, v159
	ds_bpermute_b32 v160, v212, v160
	ds_bpermute_b32 v161, v212, v161
	s_waitcnt lgkmcnt(8)
	v_mov_b32_e32 v192, 0
	v_mov_b32_e32 v193, 0
	v_lshlrev_b32_e32 v204, 16, v154
	v_and_b32_e32 v205, 0xffff0000, v154
	v_pk_add_f32 v[76:77], v[76:77], v[204:205]
	v_pk_fma_f32 v[192:193], v[76:77], v[76:77], v[192:193]
	v_lshlrev_b32_e32 v190, 16, v155
	v_and_b32_e32 v191, 0xffff0000, v155
	v_pk_add_f32 v[78:79], v[78:79], v[190:191]
	v_pk_fma_f32 v[192:193], v[78:79], v[78:79], v[192:193]
	v_lshlrev_b32_e32 v204, 16, v156
	v_and_b32_e32 v205, 0xffff0000, v156
	v_pk_add_f32 v[72:73], v[72:73], v[204:205]
	v_pk_fma_f32 v[192:193], v[72:73], v[72:73], v[192:193]
	v_lshlrev_b32_e32 v190, 16, v157
	v_and_b32_e32 v191, 0xffff0000, v157
	v_pk_add_f32 v[74:75], v[74:75], v[190:191]
	v_pk_fma_f32 v[192:193], v[74:75], v[74:75], v[192:193]
	v_cvt_pk_bf16_f32 v76, v76, v77
	v_cvt_pk_bf16_f32 v77, v78, v79
	v_cvt_pk_bf16_f32 v78, v72, v73
	v_cvt_pk_bf16_f32 v79, v74, v75
	ds_bpermute_b32 v72, v213, v76
	ds_bpermute_b32 v73, v213, v77
	ds_bpermute_b32 v74, v213, v78
	ds_bpermute_b32 v75, v213, v79
	s_waitcnt lgkmcnt(8)
	global_store_dwordx4 v234, v[80:83], s[30:31] offset:256
	s_add_u32 s30, s30, 0x8000
	s_addc_u32 s31, s31, 0
	s_waitcnt vmcnt(13)
	ds_bpermute_b32 v162, v212, v162
	ds_bpermute_b32 v163, v212, v163
	ds_bpermute_b32 v164, v212, v164
	ds_bpermute_b32 v165, v212, v165
	s_waitcnt lgkmcnt(8)
	v_lshlrev_b32_e32 v204, 16, v158
	v_and_b32_e32 v205, 0xffff0000, v158
	v_pk_add_f32 v[68:69], v[68:69], v[204:205]
	v_pk_fma_f32 v[192:193], v[68:69], v[68:69], v[192:193]
	v_lshlrev_b32_e32 v190, 16, v159
	v_and_b32_e32 v191, 0xffff0000, v159
	v_pk_add_f32 v[70:71], v[70:71], v[190:191]
	v_pk_fma_f32 v[192:193], v[70:71], v[70:71], v[192:193]
	v_lshlrev_b32_e32 v204, 16, v160
	v_and_b32_e32 v205, 0xffff0000, v160
	v_pk_add_f32 v[64:65], v[64:65], v[204:205]
	v_pk_fma_f32 v[192:193], v[64:65], v[64:65], v[192:193]
	v_lshlrev_b32_e32 v190, 16, v161
	v_and_b32_e32 v191, 0xffff0000, v161
	v_pk_add_f32 v[66:67], v[66:67], v[190:191]
	v_pk_fma_f32 v[192:193], v[66:67], v[66:67], v[192:193]
	v_cvt_pk_bf16_f32 v68, v68, v69
	v_cvt_pk_bf16_f32 v69, v70, v71
	v_cvt_pk_bf16_f32 v70, v64, v65
	v_cvt_pk_bf16_f32 v71, v66, v67
	ds_bpermute_b32 v64, v213, v68
	ds_bpermute_b32 v65, v213, v69
	ds_bpermute_b32 v66, v213, v70
	ds_bpermute_b32 v67, v213, v71
	v_add_f32_e32 v154, v192, v193
	s_waitcnt lgkmcnt(8)
	global_store_dwordx4 v234, v[72:75], s[30:31]
	s_waitcnt vmcnt(13)
	ds_bpermute_b32 v166, v212, v166
	ds_bpermute_b32 v167, v212, v167
	ds_bpermute_b32 v168, v212, v168
	ds_bpermute_b32 v169, v212, v169
	s_waitcnt lgkmcnt(8)
	v_mov_b32_e32 v192, 0
	v_mov_b32_e32 v193, 0
	v_lshlrev_b32_e32 v204, 16, v162
	v_and_b32_e32 v205, 0xffff0000, v162
	v_pk_add_f32 v[60:61], v[60:61], v[204:205]
	v_pk_fma_f32 v[192:193], v[60:61], v[60:61], v[192:193]
	v_lshlrev_b32_e32 v190, 16, v163
	v_and_b32_e32 v191, 0xffff0000, v163
	v_pk_add_f32 v[62:63], v[62:63], v[190:191]
	v_pk_fma_f32 v[192:193], v[62:63], v[62:63], v[192:193]
	v_lshlrev_b32_e32 v204, 16, v164
	v_and_b32_e32 v205, 0xffff0000, v164
	v_pk_add_f32 v[56:57], v[56:57], v[204:205]
	v_pk_fma_f32 v[192:193], v[56:57], v[56:57], v[192:193]
	v_lshlrev_b32_e32 v190, 16, v165
	v_and_b32_e32 v191, 0xffff0000, v165
	v_pk_add_f32 v[58:59], v[58:59], v[190:191]
	v_pk_fma_f32 v[192:193], v[58:59], v[58:59], v[192:193]
	v_cvt_pk_bf16_f32 v60, v60, v61
	v_cvt_pk_bf16_f32 v61, v62, v63
	v_cvt_pk_bf16_f32 v62, v56, v57
	v_cvt_pk_bf16_f32 v63, v58, v59
	ds_bpermute_b32 v56, v213, v60
	ds_bpermute_b32 v57, v213, v61
	ds_bpermute_b32 v58, v213, v62
	ds_bpermute_b32 v59, v213, v63
	s_waitcnt lgkmcnt(8)
	global_store_dwordx4 v234, v[64:67], s[30:31] offset:256
	s_add_u32 s30, s30, 0x28000
	s_addc_u32 s31, s31, 0
	s_waitcnt vmcnt(13)
	ds_bpermute_b32 v182, v212, v182
	ds_bpermute_b32 v183, v212, v183
	ds_bpermute_b32 v184, v212, v184
	ds_bpermute_b32 v185, v212, v185
	s_waitcnt lgkmcnt(8)
	v_lshlrev_b32_e32 v204, 16, v166
	v_and_b32_e32 v205, 0xffff0000, v166
	v_pk_add_f32 v[52:53], v[52:53], v[204:205]
	v_pk_fma_f32 v[192:193], v[52:53], v[52:53], v[192:193]
	v_lshlrev_b32_e32 v190, 16, v167
	v_and_b32_e32 v191, 0xffff0000, v167
	v_pk_add_f32 v[54:55], v[54:55], v[190:191]
	v_pk_fma_f32 v[192:193], v[54:55], v[54:55], v[192:193]
	v_lshlrev_b32_e32 v204, 16, v168
	v_and_b32_e32 v205, 0xffff0000, v168
	v_pk_add_f32 v[48:49], v[48:49], v[204:205]
	v_pk_fma_f32 v[192:193], v[48:49], v[48:49], v[192:193]
	v_lshlrev_b32_e32 v190, 16, v169
	v_and_b32_e32 v191, 0xffff0000, v169
	v_pk_add_f32 v[50:51], v[50:51], v[190:191]
	v_pk_fma_f32 v[192:193], v[50:51], v[50:51], v[192:193]
	v_cvt_pk_bf16_f32 v52, v52, v53
	v_cvt_pk_bf16_f32 v53, v54, v55
	v_cvt_pk_bf16_f32 v54, v48, v49
	v_cvt_pk_bf16_f32 v55, v50, v51
	ds_bpermute_b32 v48, v213, v52
	ds_bpermute_b32 v49, v213, v53
	ds_bpermute_b32 v50, v213, v54
	ds_bpermute_b32 v51, v213, v55
	v_add_f32_e32 v162, v192, v193
	s_waitcnt lgkmcnt(8)
	global_store_dwordx4 v234, v[56:59], s[30:31]
	s_waitcnt vmcnt(13)
	ds_bpermute_b32 v186, v212, v186
	ds_bpermute_b32 v187, v212, v187
	ds_bpermute_b32 v188, v212, v188
	ds_bpermute_b32 v189, v212, v189
	s_waitcnt lgkmcnt(8)
	v_mov_b32_e32 v192, 0
	v_mov_b32_e32 v193, 0
	v_lshlrev_b32_e32 v204, 16, v182
	v_and_b32_e32 v205, 0xffff0000, v182
	v_pk_add_f32 v[44:45], v[44:45], v[204:205]
	v_pk_fma_f32 v[192:193], v[44:45], v[44:45], v[192:193]
	v_lshlrev_b32_e32 v190, 16, v183
	v_and_b32_e32 v191, 0xffff0000, v183
	v_pk_add_f32 v[46:47], v[46:47], v[190:191]
	v_pk_fma_f32 v[192:193], v[46:47], v[46:47], v[192:193]
	v_lshlrev_b32_e32 v204, 16, v184
	v_and_b32_e32 v205, 0xffff0000, v184
	v_pk_add_f32 v[40:41], v[40:41], v[204:205]
	v_pk_fma_f32 v[192:193], v[40:41], v[40:41], v[192:193]
	v_lshlrev_b32_e32 v190, 16, v185
	v_and_b32_e32 v191, 0xffff0000, v185
	v_pk_add_f32 v[42:43], v[42:43], v[190:191]
	v_pk_fma_f32 v[192:193], v[42:43], v[42:43], v[192:193]
	v_cvt_pk_bf16_f32 v44, v44, v45
	v_cvt_pk_bf16_f32 v45, v46, v47
	v_cvt_pk_bf16_f32 v46, v40, v41
	v_cvt_pk_bf16_f32 v47, v42, v43
	ds_bpermute_b32 v40, v213, v44
	ds_bpermute_b32 v41, v213, v45
	ds_bpermute_b32 v42, v213, v46
	ds_bpermute_b32 v43, v213, v47
	s_waitcnt lgkmcnt(8)
	global_store_dwordx4 v234, v[48:51], s[30:31] offset:256
	s_add_u32 s30, s30, 0x8000
	s_addc_u32 s31, s31, 0
	s_waitcnt vmcnt(13)
	ds_bpermute_b32 v200, v212, v200
	ds_bpermute_b32 v201, v212, v201
	ds_bpermute_b32 v202, v212, v202
	ds_bpermute_b32 v203, v212, v203
	s_waitcnt lgkmcnt(8)
	v_lshlrev_b32_e32 v204, 16, v186
	v_and_b32_e32 v205, 0xffff0000, v186
	v_pk_add_f32 v[36:37], v[36:37], v[204:205]
	v_pk_fma_f32 v[192:193], v[36:37], v[36:37], v[192:193]
	v_lshlrev_b32_e32 v190, 16, v187
	v_and_b32_e32 v191, 0xffff0000, v187
	v_pk_add_f32 v[38:39], v[38:39], v[190:191]
	v_pk_fma_f32 v[192:193], v[38:39], v[38:39], v[192:193]
	v_lshlrev_b32_e32 v204, 16, v188
	v_and_b32_e32 v205, 0xffff0000, v188
	v_pk_add_f32 v[32:33], v[32:33], v[204:205]
	v_pk_fma_f32 v[192:193], v[32:33], v[32:33], v[192:193]
	v_lshlrev_b32_e32 v190, 16, v189
	v_and_b32_e32 v191, 0xffff0000, v189
	v_pk_add_f32 v[34:35], v[34:35], v[190:191]
	v_pk_fma_f32 v[192:193], v[34:35], v[34:35], v[192:193]
	v_cvt_pk_bf16_f32 v36, v36, v37
	v_cvt_pk_bf16_f32 v37, v38, v39
	v_cvt_pk_bf16_f32 v38, v32, v33
	v_cvt_pk_bf16_f32 v39, v34, v35
	ds_bpermute_b32 v32, v213, v36
	ds_bpermute_b32 v33, v213, v37
	ds_bpermute_b32 v34, v213, v38
	ds_bpermute_b32 v35, v213, v39
	v_add_f32_e32 v182, v192, v193
	s_waitcnt lgkmcnt(8)
	global_store_dwordx4 v234, v[40:43], s[30:31]
	s_waitcnt vmcnt(13)
	ds_bpermute_b32 v208, v212, v208
	ds_bpermute_b32 v209, v212, v209
	ds_bpermute_b32 v210, v212, v210
	ds_bpermute_b32 v211, v212, v211
	s_waitcnt lgkmcnt(8)
	v_mov_b32_e32 v192, 0
	v_mov_b32_e32 v193, 0
	v_lshlrev_b32_e32 v204, 16, v200
	v_and_b32_e32 v205, 0xffff0000, v200
	v_pk_add_f32 v[28:29], v[28:29], v[204:205]
	v_pk_fma_f32 v[192:193], v[28:29], v[28:29], v[192:193]
	v_lshlrev_b32_e32 v190, 16, v201
	v_and_b32_e32 v191, 0xffff0000, v201
	v_pk_add_f32 v[30:31], v[30:31], v[190:191]
	v_pk_fma_f32 v[192:193], v[30:31], v[30:31], v[192:193]
	v_lshlrev_b32_e32 v204, 16, v202
	v_and_b32_e32 v205, 0xffff0000, v202
	v_pk_add_f32 v[24:25], v[24:25], v[204:205]
	v_pk_fma_f32 v[192:193], v[24:25], v[24:25], v[192:193]
	v_lshlrev_b32_e32 v190, 16, v203
	v_and_b32_e32 v191, 0xffff0000, v203
	v_pk_add_f32 v[26:27], v[26:27], v[190:191]
	v_pk_fma_f32 v[192:193], v[26:27], v[26:27], v[192:193]
	v_cvt_pk_bf16_f32 v28, v28, v29
	v_cvt_pk_bf16_f32 v29, v30, v31
	v_cvt_pk_bf16_f32 v30, v24, v25
	v_cvt_pk_bf16_f32 v31, v26, v27
	ds_bpermute_b32 v24, v213, v28
	ds_bpermute_b32 v25, v213, v29
	ds_bpermute_b32 v26, v213, v30
	ds_bpermute_b32 v27, v213, v31
	s_waitcnt lgkmcnt(8)
	global_store_dwordx4 v234, v[32:35], s[30:31] offset:256
	s_add_u32 s30, s30, 0x8000
	s_addc_u32 s31, s31, 0
	s_waitcnt vmcnt(13)
	ds_bpermute_b32 v226, v212, v226
	ds_bpermute_b32 v227, v212, v227
	ds_bpermute_b32 v228, v212, v228
	ds_bpermute_b32 v229, v212, v229
	s_waitcnt lgkmcnt(8)
	v_lshlrev_b32_e32 v204, 16, v208
	v_and_b32_e32 v205, 0xffff0000, v208
	v_pk_add_f32 v[20:21], v[20:21], v[204:205]
	v_pk_fma_f32 v[192:193], v[20:21], v[20:21], v[192:193]
	v_lshlrev_b32_e32 v190, 16, v209
	v_and_b32_e32 v191, 0xffff0000, v209
	v_pk_add_f32 v[22:23], v[22:23], v[190:191]
	v_pk_fma_f32 v[192:193], v[22:23], v[22:23], v[192:193]
	v_lshlrev_b32_e32 v204, 16, v210
	v_and_b32_e32 v205, 0xffff0000, v210
	v_pk_add_f32 v[16:17], v[16:17], v[204:205]
	v_pk_fma_f32 v[192:193], v[16:17], v[16:17], v[192:193]
	v_lshlrev_b32_e32 v190, 16, v211
	v_and_b32_e32 v191, 0xffff0000, v211
	v_pk_add_f32 v[18:19], v[18:19], v[190:191]
	v_pk_fma_f32 v[192:193], v[18:19], v[18:19], v[192:193]
	v_cvt_pk_bf16_f32 v20, v20, v21
	v_cvt_pk_bf16_f32 v21, v22, v23
	v_cvt_pk_bf16_f32 v22, v16, v17
	v_cvt_pk_bf16_f32 v23, v18, v19
	ds_bpermute_b32 v16, v213, v20
	ds_bpermute_b32 v17, v213, v21
	ds_bpermute_b32 v18, v213, v22
	ds_bpermute_b32 v19, v213, v23
	v_add_f32_e32 v200, v192, v193
	s_waitcnt lgkmcnt(8)
	global_store_dwordx4 v234, v[24:27], s[30:31]
	s_waitcnt vmcnt(13)
	ds_bpermute_b32 v230, v212, v230
	ds_bpermute_b32 v231, v212, v231
	ds_bpermute_b32 v232, v212, v232
	ds_bpermute_b32 v233, v212, v233
	s_waitcnt lgkmcnt(8)
	v_mov_b32_e32 v192, 0
	v_mov_b32_e32 v193, 0
	v_lshlrev_b32_e32 v204, 16, v226
	v_and_b32_e32 v205, 0xffff0000, v226
	v_pk_add_f32 v[12:13], v[12:13], v[204:205]
	v_pk_fma_f32 v[192:193], v[12:13], v[12:13], v[192:193]
	v_lshlrev_b32_e32 v190, 16, v227
	v_and_b32_e32 v191, 0xffff0000, v227
	v_pk_add_f32 v[14:15], v[14:15], v[190:191]
	v_pk_fma_f32 v[192:193], v[14:15], v[14:15], v[192:193]
	v_lshlrev_b32_e32 v204, 16, v228
	v_and_b32_e32 v205, 0xffff0000, v228
	v_pk_add_f32 v[8:9], v[8:9], v[204:205]
	v_pk_fma_f32 v[192:193], v[8:9], v[8:9], v[192:193]
	v_lshlrev_b32_e32 v190, 16, v229
	v_and_b32_e32 v191, 0xffff0000, v229
	v_pk_add_f32 v[10:11], v[10:11], v[190:191]
	v_pk_fma_f32 v[192:193], v[10:11], v[10:11], v[192:193]
	v_cvt_pk_bf16_f32 v12, v12, v13
	v_cvt_pk_bf16_f32 v13, v14, v15
	v_cvt_pk_bf16_f32 v14, v8, v9
	v_cvt_pk_bf16_f32 v15, v10, v11
	ds_bpermute_b32 v8, v213, v12
	ds_bpermute_b32 v9, v213, v13
	ds_bpermute_b32 v10, v213, v14
	ds_bpermute_b32 v11, v213, v15
	s_waitcnt lgkmcnt(8)
	global_store_dwordx4 v234, v[16:19], s[30:31] offset:256
	s_add_u32 s30, s30, 0x8000
	s_addc_u32 s31, s31, 0
	s_waitcnt lgkmcnt(4)
	v_lshlrev_b32_e32 v204, 16, v230
	v_and_b32_e32 v205, 0xffff0000, v230
	v_pk_add_f32 v[4:5], v[4:5], v[204:205]
	v_pk_fma_f32 v[192:193], v[4:5], v[4:5], v[192:193]
	v_lshlrev_b32_e32 v190, 16, v231
	v_and_b32_e32 v191, 0xffff0000, v231
	v_pk_add_f32 v[6:7], v[6:7], v[190:191]
	v_pk_fma_f32 v[192:193], v[6:7], v[6:7], v[192:193]
	v_lshlrev_b32_e32 v204, 16, v232
	v_and_b32_e32 v205, 0xffff0000, v232
	v_pk_add_f32 v[0:1], v[0:1], v[204:205]
	v_pk_fma_f32 v[192:193], v[0:1], v[0:1], v[192:193]
	v_lshlrev_b32_e32 v190, 16, v233
	v_and_b32_e32 v191, 0xffff0000, v233
	v_pk_add_f32 v[2:3], v[2:3], v[190:191]
	v_pk_fma_f32 v[192:193], v[2:3], v[2:3], v[192:193]
	v_cvt_pk_bf16_f32 v4, v4, v5
	v_cvt_pk_bf16_f32 v5, v6, v7
	v_cvt_pk_bf16_f32 v6, v0, v1
	v_cvt_pk_bf16_f32 v7, v2, v3
	ds_bpermute_b32 v0, v213, v4
	ds_bpermute_b32 v1, v213, v5
	ds_bpermute_b32 v2, v213, v6
	ds_bpermute_b32 v3, v213, v7
	v_add_f32_e32 v226, v192, v193
	s_waitcnt lgkmcnt(4)
	global_store_dwordx4 v234, v[8:11], s[30:31]
	s_waitcnt lgkmcnt(0)
	global_store_dwordx4 v234, v[0:3], s[30:31] offset:256
	ds_swizzle_b32 v131, v130 offset:swizzle(SWAP,16)
	ds_swizzle_b32 v139, v138 offset:swizzle(SWAP,16)
	ds_swizzle_b32 v147, v146 offset:swizzle(SWAP,16)
	ds_swizzle_b32 v155, v154 offset:swizzle(SWAP,16)
	ds_swizzle_b32 v163, v162 offset:swizzle(SWAP,16)
	ds_swizzle_b32 v183, v182 offset:swizzle(SWAP,16)
	ds_swizzle_b32 v201, v200 offset:swizzle(SWAP,16)
	ds_swizzle_b32 v227, v226 offset:swizzle(SWAP,16)
	s_lshl_b32 s30, s1, 2
	s_add_u32 s30, s14, s30
	s_addc_u32 s31, s15, 0
	s_waitcnt lgkmcnt(0)
	v_add_f32_e32 v130, v130, v131
	v_mov_b32_e32 v131, v130
	v_add_f32_e32 v138, v138, v139
	v_mov_b32_e32 v139, v138
	v_add_f32_e32 v146, v146, v147
	v_mov_b32_e32 v147, v146
	v_add_f32_e32 v154, v154, v155
	v_mov_b32_e32 v155, v154
	v_add_f32_e32 v162, v162, v163
	v_mov_b32_e32 v163, v162
	v_add_f32_e32 v182, v182, v183
	v_mov_b32_e32 v183, v182
	v_add_f32_e32 v200, v200, v201
	v_mov_b32_e32 v201, v200
	v_add_f32_e32 v226, v226, v227
	v_mov_b32_e32 v227, v226
	s_nop 1
	v_permlane32_swap_b32_e32 v130, v131
	v_permlane32_swap_b32_e32 v138, v139
	v_permlane32_swap_b32_e32 v146, v147
	v_permlane32_swap_b32_e32 v154, v155
	v_permlane32_swap_b32_e32 v162, v163
	v_permlane32_swap_b32_e32 v182, v183
	v_permlane32_swap_b32_e32 v200, v201
	v_permlane32_swap_b32_e32 v226, v227
	s_and_saveexec_b64 s[28:29], s[78:79]
	v_add_f32_e32 v130, v130, v131
	v_add_f32_e32 v138, v138, v139
	v_add_f32_e32 v146, v146, v147
	v_add_f32_e32 v154, v154, v155
	v_add_f32_e32 v162, v162, v163
	v_add_f32_e32 v182, v182, v183
	v_add_f32_e32 v200, v200, v201
	v_add_f32_e32 v226, v226, v227
	global_atomic_add_f32 v100, v130, s[30:31]
	global_atomic_add_f32 v100, v138, s[30:31] offset:64
	global_atomic_add_f32 v100, v146, s[30:31] offset:128
	global_atomic_add_f32 v100, v154, s[30:31] offset:192
	global_atomic_add_f32 v100, v162, s[30:31] offset:512
	global_atomic_add_f32 v100, v182, s[30:31] offset:576
	global_atomic_add_f32 v100, v200, s[30:31] offset:640
	global_atomic_add_f32 v100, v226, s[30:31] offset:704
	s_or_b64 exec, exec, s[28:29]
	s_mov_b64 s[30:31], exec
	s_branch .LBB0_218
